# attention K LDS tile: 4-bit XOR swizzle so QK^T ds_read_b128 fragments are bank-conflict-free
# speedup vs baseline: 1.0110x; 1.0030x over previous
; __device__ __forceinline__ float wave_sum(float v, int lane) {
; #pragma unroll
;     for (int o = 1; o < 64; o <<= 1) v += __builtin_bit_cast(float, __builtin_amdgcn_ds_bpermute((lane ^ o) << 2, __builtin_bit_cast(int, v)));
;     return v;
; }
; __global__ void __launch_bounds__(NWAVES * 64) mega_fwd(Args args) {
;     ...
;         const float lam = __expf(wave_sum(lq1[lane] * lk1[lane], lane)) - __expf(wave_sum(lq2[lane] * lk2[lane], lane)) + 0.2f;
;         for (int i = 0, U = vcu; U < BATCH * NH * (SEQ / 128); U += G, ++i) {
;             int b = U >> 7, h = (U >> 4) & 7, qb = U & 15;
;             if (G == 256) { const int gi = vcu >> 4; h = (gi + i) & 7; b = i * 2 + (gi >> 3); qb = (vcu + i) & 15; }
;             attn::attn_unit_pp(b, h, qb, i & 1, QB, KB, VB, GB, HB, PLD, Wt_pl, lam, sub_g, NRMK, (char*)lds);
;         }
.LBB0_336:
	s_or_b64 exec, exec, s[0:1]
	s_waitcnt lgkmcnt(0)
	v_lshlrev_b32_e32 v0, 2, v45
	s_barrier
	global_load_dword v1, v0, s[46:47]
	global_load_dword v2, v0, s[48:49]
	global_load_dword v3, v0, s[50:51]
	global_load_dword v4, v0, s[52:53]
	v_xor_b32_e32 v5, 4, v0
	s_cmpk_gt_i32 s40, 0xfff
	s_waitcnt vmcnt(2)
	v_mul_f32_e32 v6, v1, v2
	ds_bpermute_b32 v6, v5, v6
	s_waitcnt vmcnt(0)
	v_mul_f32_e32 v7, v3, v4
	ds_bpermute_b32 v5, v5, v7
	v_xor_b32_e32 v7, 8, v0
	s_waitcnt lgkmcnt(1)
	v_fmac_f32_e32 v6, v1, v2
	ds_bpermute_b32 v1, v7, v6
	s_waitcnt lgkmcnt(1)
	v_fmac_f32_e32 v5, v3, v4
	ds_bpermute_b32 v2, v7, v5
	v_xor_b32_e32 v3, 16, v0
	s_waitcnt lgkmcnt(1)
	v_add_f32_e32 v1, v6, v1
	ds_bpermute_b32 v4, v3, v1
	s_waitcnt lgkmcnt(1)
	v_add_f32_e32 v2, v5, v2
	ds_bpermute_b32 v3, v3, v2
	v_xor_b32_e32 v5, 32, v0
	s_waitcnt lgkmcnt(1)
	v_add_f32_e32 v1, v1, v4
	s_waitcnt lgkmcnt(0)
	v_add_f32_e32 v2, v2, v3
	ds_bpermute_b32 v3, v5, v1
	ds_bpermute_b32 v4, v5, v2
	v_xor_b32_e32 v5, 64, v0
	s_waitcnt lgkmcnt(1)
	v_add_f32_e32 v1, v1, v3
	s_waitcnt lgkmcnt(0)
	v_add_f32_e32 v2, v2, v4
	ds_bpermute_b32 v3, v5, v1
	ds_bpermute_b32 v4, v5, v2
	v_xor_b32_e32 v5, 0x80, v0
	s_waitcnt lgkmcnt(1)
	v_add_f32_e32 v1, v1, v3
	s_waitcnt lgkmcnt(0)
	v_add_f32_e32 v0, v2, v4
	ds_bpermute_b32 v3, v5, v1
	ds_bpermute_b32 v2, v5, v0
	s_cbranch_scc1 .LBB0_413
	s_waitcnt lgkmcnt(1)
	v_add_f32_e32 v1, v1, v3
	s_waitcnt lgkmcnt(0)
	v_add_f32_e32 v0, v0, v2
	v_mul_f32_e32 v1, 0x3fb8aa3b, v1
	v_mul_f32_e32 v0, 0x3fb8aa3b, v0
	v_exp_f32_e32 v1, v1
	v_exp_f32_e32 v0, v0
	s_cmpk_eq_i32 s70, 0x100
	s_cselect_b64 s[4:5], -1, 0
	s_lshr_b32 s9, s40, 4
	v_sub_f32_e32 v0, v1, v0
	v_add_f32_e32 v175, 0x3e4ccccd, v0
	s_ashr_i32 s35, s40, 7
	s_mov_b32 s7, 0
	v_mov_b32_e32 v1, 0
	s_movk_i32 s41, 0xf0
	s_mov_b32 s48, 0x8000
	s_mov_b32 s49, 0xf800000
	v_mov_b32_e32 v176, 0x260
	s_mov_b32 s50, 0x3f828f5c
	s_mov_b32 s51, 0x42fc0000
	s_mov_b32 s8, 0x3c800000
	s_mov_b32 s52, 0x44ffe000
	s_add_i32 s53, 0, 0x10000
	s_movk_i32 s58, 0x4000
	v_mov_b32_e32 v166, 0xc2200000
	s_mov_b32 s59, 0x41380000
	s_add_i32 s60, 0, 0x10800
	s_movk_i32 s61, 0x2000
	v_mov_b32_e32 v177, 0x3727c5ac
	s_movk_i32 s66, 0x7fff
	s_movk_i32 s67, 0x6000
	v_mov_b32_e32 v178, 0x42800000
	s_mov_b32 s82, 0
	s_mov_b32 s83, s40
	s_branch .LBB0_339

; __device__ __forceinline__ int v_st(int k, int c) { const int kk = (k & ~0xC) | ((k & 4) << 1) | ((k & 8) >> 1); return ((kk >> 3) * 4 + (c >> 5)) * 512 + ((kk & 7) * 32 + (c & 31)) * 2; }
; __device__ __forceinline__ void attn_unit_pp(int b, int h, int qb, int par, const bf16_t* __restrict__ QBp, const bf16_t* __restrict__ KBp, const bf16_t* __restrict__ VBp, ...
;     ...
;   const int tid = tid_, wid = tid >> 6, lane = tid & 63, r32 = lane & 31, hi = lane >> 5, w4 = wid & 3, t256 = tid & 255;
;   const int g = __builtin_amdgcn_readfirstlane(tid >> 8);
;   const long rowbase = (long)b * SEQ; const int q0 = qb * 128;
;   const size_t hoff = HEADMAJOR ? (size_t)(b * 8 + h) * SEQ * 128 : (size_t)b * SEQ * 1024 + h * 128;
;   const bf16_t* Kh = KBp + hoff; const bf16_t* Vh = VBp + hoff;
;   char* V_lds = lds; char* K_lds = lds + 2 * SHM_V;
;   float* wsf = (float*)(lds + 2 * SHM_V + 2 * SHM_K) + wid * 64; float* li_l = wsf; float* al_l = wsf + 32;
;   const float nslope = -exp2f(-(float)(h + 1)) * 1.4426950408889634f;
;   const bf16_t* Qw = QBp + hoff + (size_t)(q0 + w4 * QBLK + r32) * LD + g * 64 + hi * 8;
;   bf16x8 qr[4];
; #pragma unroll
;   for (int d0 = 0; d0 < 4; ++d0) qr[d0] = ld8(Qw + d0 * 16);
;   const float qposf = (float)(q0 + w4 * QBLK + r32 - 4 * hi);
;   const int sr = t256 >> 4, sc = (t256 & 15) * 8;
;   int woff[4];
; #pragma unroll
;   for (int i = 0; i < 4; ++i) { const int row = sr + 16 * i; woff[i] = g ? (int)(2 * SHM_V) + KSWZ(row, sc * 2) : v_st(row, sc); }
.LBB0_339:
	s_lshl_b32 s0, s82, 1
	s_ashr_i32 s2, s83, 7
	s_lshr_b32 s3, s83, 4
	s_add_i32 s6, s82, s9
	s_add_i32 s10, s0, s35
	s_add_i32 s11, s82, s40
	s_and_b64 s[0:1], s[4:5], exec
	s_cselect_b32 s0, s11, s83
	s_cselect_b32 s1, s6, s3
	s_cselect_b32 s10, s10, s2
	s_and_b32 s6, s1, 7
	s_and_b32 s22, s0, 15
	v_mov_b32_e32 v4, v174
	s_lshl_b32 s0, s10, 3
	s_or_b32 s16, s0, s6
	v_ashrrev_i32_e32 v3, 6, v4
	v_and_b32_e32 v184, 3, v3
	v_readfirstlane_b32 s2, v4
	s_ashr_i32 s17, s16, 31
	v_and_b32_e32 v179, 31, v4
	s_ashr_i32 s38, s2, 8
	s_lshl_b32 s84, s22, 7
	s_lshl_b64 s[0:1], s[16:17], 19
	v_lshlrev_b32_e32 v185, 5, v184
	s_add_u32 s0, s18, s0
	v_or3_b32 v5, v179, s84, v185
	s_addc_u32 s1, s19, s1
	v_lshlrev_b32_e32 v0, 8, v5
	s_lshl_b32 s46, s38, 6
	v_bfe_u32 v6, v4, 5, 1
	v_lshl_add_u64 v[8:9], s[0:1], 0, v[0:1]
	s_ashr_i32 s47, s46, 31
	v_lshl_add_u64 v[8:9], s[46:47], 1, v[8:9]
	v_lshlrev_b32_e32 v0, 4, v6
	v_lshl_add_u64 v[8:9], v[8:9], 0, v[0:1]
	global_load_dwordx4 v[130:133], v[8:9], off
	global_load_dwordx4 v[134:137], v[8:9], off offset:32
	global_load_dwordx4 v[138:141], v[8:9], off offset:64
	global_load_dwordx4 v[142:145], v[8:9], off offset:96
	v_lshlrev_b32_e32 v8, 3, v4
	v_and_b32_e32 v2, 0x78, v8
	s_cmpk_lt_u32 s2, 0x100
	v_lshlrev_b32_e32 v2, 1, v2
	v_and_b32_e32 v9, 0xf0, v4
	v_bfe_u32 v7, v4, 4, 4
	s_cselect_b64 s[12:13], -1, 0
	s_cmpk_gt_u32 s2, 0xff
	v_bitop3_b32 v10, v2, s48, v9 bitop3:0xde
	s_cselect_b64 s[2:3], -1, 0
	s_and_b64 vcc, exec, s[12:13]
	v_lshl_or_b32 v16, v7, 8, v10
	s_mov_b64 s[0:1], -1
	s_cbranch_vccnz .LBB0_341
	v_lshl_or_b32 v17, v7, 8, v10
	s_mov_b64 s[0:1], 0

; __device__ __forceinline__ void attn_unit_pp(int b, int h, int qb, int par, const bf16_t* __restrict__ QBp, const bf16_t* __restrict__ KBp, const bf16_t* __restrict__ VBp, ...
;     ...
;   float* wsf = (float*)(lds + 2 * SHM_V + 2 * SHM_K) + wid * 64; float* li_l = wsf; float* al_l = wsf + 32;
;   const float nslope = -exp2f(-(float)(h + 1)) * 1.4426950408889634f;
;   const bf16_t* Qw = QBp + hoff + (size_t)(q0 + w4 * QBLK + r32) * LD + g * 64 + hi * 8;
;   bf16x8 qr[4];
; #pragma unroll
;   for (int d0 = 0; d0 < 4; ++d0) qr[d0] = ld8(Qw + d0 * 16);
;   const float qposf = (float)(q0 + w4 * QBLK + r32 - 4 * hi);
;   const int sr = t256 >> 4, sc = (t256 & 15) * 8;
;   int woff[4];
; #pragma unroll
;   for (int i = 0; i < 4; ++i) { const int row = sr + 16 * i; woff[i] = g ? (int)(2 * SHM_V) + KSWZ(row, sc * 2) : v_st(row, sc); }
;   const bf16_t* Tsrc = (g ? Kh : Vh) + (long)sr * LD + sc;
;   const char* Kmine = K_lds + g * 128;
;   const int vb0 = (int)(uintptr_t)V_lds + v_rd_base(lane);
;   float m_reg = 0.f, l_reg = 0.f, alpha = 1.f; f32x16 o[4]; f32x16 negm = f32x16{}; f32x16 p0, p1; bf16x8 pa0, pa1, pa2, pa3; bf16x8 stg[4];
; #pragma unroll
;   for (int d = 0; d < 4; ++d) o[d] = f32x16{};
;   constexpr int NT = SEQ / KVBLK;
;   float qn = 0.f;
; #pragma unroll
;   for (int d0 = 0; d0 < 4; ++d0) { const u32x4 w = __builtin_bit_cast(u32x4, qr[d0]);
; #pragma unroll
;     for (int e = 0; e < 4; ++e) { const float lo = __uint_as_float(w[e] << 16), hh = __uint_as_float(w[e] & 0xffff0000u); qn = fmaf(lo, lo, qn); qn = fmaf(hh, hh, qn); } }
;   { auto rr = __builtin_amdgcn_permlane32_swap(__float_as_uint(qn), __float_as_uint(qn), false, false); qn = __uint_as_float(rr[0]) + __uint_as_float(rr[1]); }
;   float sii = 0.f;
;   { const bf16_t* Kw = Kh + (size_t)(q0 + w4 * QBLK + r32) * LD + g * 64 + hi * 8;
; #pragma unroll
;     for (int d0 = 0; d0 < 4; ++d0) { const u32x4 wq = __builtin_bit_cast(u32x4, qr[d0]); const u32x4 wk = __builtin_bit_cast(u32x4, ld8(Kw + d0 * 16));
; #pragma unroll
;       for (int e = 0; e < 4; ++e) { sii = fmaf(__uint_as_float(wq[e] << 16), __uint_as_float(wk[e] << 16), sii); sii = fmaf(__uint_as_float(wq[e] & 0xffff0000u), __uint_as_float(wk[e] & 0xffff0000u), sii); } } }
;   { auto rr = __builtin_amdgcn_permlane32_swap(__float_as_uint(sii), __float_as_uint(sii), false, false); sii = __uint_as_float(rr[0]) + __uint_as_float(rr[1]); }
.LBB0_362:
	v_lshlrev_b32_e32 v3, 4, v186
	v_lshlrev_b32_e32 v188, 2, v6
	v_lshlrev_b32_e32 v2, 3, v186
	v_and_b32_e32 v3, 0xc0, v3
	v_lshlrev_b32_e32 v6, 1, v186
	v_and_or_b32 v3, v2, 24, v3
	v_and_b32_e32 v6, 32, v6
	v_and_b32_e32 v2, 0x100, v2
	v_or3_b32 v191, v3, v6, v2
	v_and_b32_e32 v2, 0x3fffffc0, v4
	v_lshl_add_u32 v2, v2, 2, s53
	s_mov_b32 s46, 0
	s_cmp_lt_i32 s11, 0
	v_cmp_gt_u32_e64 s[2:3], 32, v186
	v_lshl_add_u32 v190, v179, 2, v2
	v_lshl_add_u32 v189, v188, 2, v2
	s_cbranch_scc1 .LBB0_402
	v_sub_u32_e32 v2, v5, v188
	s_lshl_b32 s14, s38, 7
	v_lshlrev_b32_e32 v3, 4, v179
	s_add_i32 s16, s14, 0
	v_cvt_f32_i32_e32 v192, v2
	v_lshlrev_b32_e32 v2, 8, v179
	v_and_b32_e32 v3, 0xf0, v3
	v_or_b32_e32 v4, 32, v0
	s_cmp_lg_u32 0, -1
	v_bitop3_b32 v20, v0, v2, v3 bitop3:0xde
	v_bitop3_b32 v21, v4, v2, v3 bitop3:0xde
	v_or_b32_e32 v4, 64, v0
	v_or_b32_e32 v0, 0x60, v0
	s_cselect_b32 s14, 0, 0
	v_bitop3_b32 v22, v4, v2, v3 bitop3:0xde
	v_bitop3_b32 v23, v0, v2, v3 bitop3:0xde
	v_mov_b32_e32 v14, v1
	v_mov_b32_e32 v15, v1
	v_add_u32_e32 v193, s14, v191
	s_addk_i32 s14, 0x4000
	s_add_i32 s38, s11, s17
	v_mov_b32_e32 v0, v1
	v_mov_b32_e32 v2, v1
	v_mov_b32_e32 v3, v1
	v_mov_b32_e32 v4, v1
	v_mov_b32_e32 v5, v1
	v_mov_b32_e32 v6, v1
	v_mov_b32_e32 v7, v1
	v_mov_b32_e32 v8, v1
	v_mov_b32_e32 v9, v1
	v_mov_b32_e32 v10, v1
	v_mov_b32_e32 v11, v1
	v_mov_b32_e32 v12, v1
	v_mov_b32_e32 v13, v1
	v_mov_b32_e32 v80, 0
	v_xor_b32_e32 v195, s16, v20
	v_xor_b32_e32 v196, s16, v21
	v_xor_b32_e32 v197, s16, v22
	v_xor_b32_e32 v198, s16, v23
	v_add_u32_e32 v199, 0, v17
	v_add_u32_e32 v200, 0, v18
	v_add_u32_e32 v201, 0, v19
	v_add_u32_e32 v202, 0, v16
	v_mov_b64_e32 v[78:79], v[14:15]
	v_mov_b64_e32 v[62:63], v[14:15]
	v_mov_b64_e32 v[46:47], v[14:15]
	v_mov_b64_e32 v[30:31], v[14:15]
	v_mov_b64_e32 v[96:97], v[14:15]
	v_add_u32_e32 v194, s14, v191
	v_mov_b32_e32 v172, 0xf149f2ca
	s_mov_b64 s[14:15], -1
	s_mov_b32 s39, s38
	v_mov_b64_e32 v[76:77], v[12:13]
	v_mov_b64_e32 v[74:75], v[10:11]
	v_mov_b64_e32 v[72:73], v[8:9]
	v_mov_b64_e32 v[70:71], v[6:7]
	v_mov_b64_e32 v[68:69], v[4:5]
	v_mov_b64_e32 v[66:67], v[2:3]
	v_mov_b64_e32 v[64:65], v[0:1]
	v_mov_b64_e32 v[60:61], v[12:13]
	v_mov_b64_e32 v[58:59], v[10:11]
	v_mov_b64_e32 v[56:57], v[8:9]
	v_mov_b64_e32 v[54:55], v[6:7]
	v_mov_b64_e32 v[52:53], v[4:5]
	v_mov_b64_e32 v[50:51], v[2:3]
	v_mov_b64_e32 v[48:49], v[0:1]
	v_mov_b64_e32 v[44:45], v[12:13]
	v_mov_b64_e32 v[42:43], v[10:11]
	v_mov_b64_e32 v[40:41], v[8:9]
	v_mov_b64_e32 v[38:39], v[6:7]
	v_mov_b64_e32 v[36:37], v[4:5]
	v_mov_b64_e32 v[34:35], v[2:3]
	v_mov_b64_e32 v[32:33], v[0:1]
	v_mov_b64_e32 v[28:29], v[12:13]
	v_mov_b64_e32 v[26:27], v[10:11]
	v_mov_b64_e32 v[24:25], v[8:9]
	v_mov_b64_e32 v[22:23], v[6:7]
	v_mov_b64_e32 v[20:21], v[4:5]
	v_mov_b64_e32 v[18:19], v[2:3]
	v_mov_b64_e32 v[16:17], v[0:1]
	v_mov_b64_e32 v[94:95], v[12:13]
	v_mov_b64_e32 v[92:93], v[10:11]
	v_mov_b64_e32 v[90:91], v[8:9]
	v_mov_b64_e32 v[88:89], v[6:7]
	v_mov_b64_e32 v[86:87], v[4:5]
	v_mov_b64_e32 v[84:85], v[2:3]
	v_mov_b64_e32 v[82:83], v[0:1]
	v_mov_b32_e32 v173, v80
